# code warming reduced to 2 KB issued line by line (8 lanes) into the unused LDS gap after the barrier state, without waiting for it before the join
# baseline (speedup 1.0000x reference)
; __device__ __forceinline__ unsigned xb_ld(unsigned* p)              { return __hip_atomic_load(p, __ATOMIC_RELAXED, __HIP_MEMORY_SCOPE_AGENT); }
; __device__ __forceinline__ unsigned xb_add(unsigned* p, unsigned v) { return __hip_atomic_fetch_add(p, v, __ATOMIC_RELAXED, __HIP_MEMORY_SCOPE_AGENT); }
; #define XB_SPIN(cond, bar) do { unsigned _sp = 0; while (cond) { __builtin_amdgcn_s_sleep(1); \
;     if ((++_sp & 255u) == 0u) { if (xb_ld(&(bar)[XB_TMO])) break; if (_sp > XB_SPIN_CAP) { atomicAdd(&(bar)[XB_TMO], 1u); break; } } } } while (0)
; __device__ __forceinline__ void xcd_barrier(const XcdBarrier& b) {
;     asm volatile("s_waitcnt vmcnt(0)" ::: "memory");
;     __syncthreads();
;     if (threadIdx.x == 0) {
;         unsigned* bar = b.bar;
;         __builtin_amdgcn_s_waitcnt(0);
;         unsigned nloc = b.st[0], nx = b.st[1];
;         if (nloc == 0u) { xcd_barrier_complete(bar, b.x, nloc, nx); b.st[0] = nloc; b.st[1] = nx; }
;         const unsigned old = xb_add(&bar[XB_XSUB(b.x)], 1u);
;         const unsigned gen = old / nloc;
;         if (old + 1u == (gen + 1u) * nloc) {
;             __builtin_amdgcn_fence(__ATOMIC_RELEASE, "agent");
;             asm volatile("s_waitcnt vmcnt(0)" ::: "memory");
;             const unsigned og = xb_add(&bar[XB_TOP], 1u);
;             const unsigned tg = og / nx;
;             if (og + 1u == (tg + 1u) * nx) xb_add(&bar[XB_TOPGEN], 1u);
;             else XB_SPIN(xb_ld(&bar[XB_TOPGEN]) == tg, bar);
;             __builtin_amdgcn_fence(__ATOMIC_ACQUIRE, "agent");
;             xb_add(&bar[XB_XGEN(b.x)], 1u);
;             asm volatile("s_waitcnt vmcnt(0)" ::: "memory");
;         } else {
;             XB_SPIN(xb_ld(&bar[XB_XGEN(b.x)]) == gen, bar);
;             __builtin_amdgcn_fence(__ATOMIC_ACQUIRE, "agent");
;             asm volatile("s_waitcnt vmcnt(0)" ::: "memory");
;         }
;     }
;     __syncthreads();
.Lwarm_pc_0:
	s_add_u32 s2, s2, .LBB0_115-.Lwarm_pc_0
	s_addc_u32 s3, s3, 0
	s_and_b32 s2, s2, 0xffffff80
	v_and_b32_e32 v0, 63, v152
	v_lshlrev_b32_e32 v0, 4, v0
	v_mov_b32_e32 v1, 0
	v_lshl_add_u64 v[0:1], s[2:3], 0, v[0:1]
	s_mov_b64 s[2:3], 0x80
	s_mov_b32 s8, 0
	s_mov_b32 m0, 0x20010
	s_mov_b64 exec, 0xff
.Lwarm_loop_0:
	global_load_lds_dwordx4 v[0:1], off
	v_lshl_add_u64 v[0:1], v[0:1], 0, s[2:3]
	s_add_u32 s8, s8, 0x80
	s_cmp_lt_u32 s8, 0x800
	s_cbranch_scc1 .Lwarm_loop_0
	s_mov_b64 exec, -1
